# MFMA/LDS interleave: attention QK^T fragment reads of a tile issued together with counted lgkmcnt waits (both attention modes)
# baseline (speedup 1.0000x reference)
; #define LAS __attribute__((address_space(3)))
; #define MFMA32(a, b, c) __builtin_amdgcn_mfma_f32_32x32x16_bf16((a), (b), (c), 0, 0, 0)
; template <int MODE> ...
;     ...
;         const float fb = slope * (float)(rr + 128 - 32 * kt);
;         f32x16 s;
; #pragma unroll
;         for (int i = 0; i < 16; ++i) s[i] = slope * (float)((i & 3) + 8 * (i >> 2)) - fb;
; #pragma unroll
;         for (int ks = 0; ks < 4; ++ks) s = MFMA32(*(const LAS bf16x8*)(kl + r * VROW + 32 * ks + 16 * h), qf[ks], s);
.LBB0_501:
	ds_read_b128 v[136:139], v130 offset:4608
	ds_read_b128 v[140:143], v130 offset:4640
	ds_read_b128 v[144:147], v130 offset:4672
	ds_read_b128 v[148:151], v130 offset:4704
	v_cvt_f32_i32_e32 v32, v135
	s_cmp_gt_i32 s77, 3
	s_mov_b64 s[96:97], -1
	v_fma_f32 v47, -v110, v32, v125
	v_fma_f32 v46, -v110, v32, v124
	v_fma_f32 v45, -v110, v32, v123
	v_fma_f32 v44, -v110, v32, v122
	v_fma_f32 v43, -v110, v32, v121
	v_fma_f32 v42, -v110, v32, v120
	v_fma_f32 v41, -v110, v32, v119
	v_fma_f32 v40, -v110, v32, v118
	v_fma_f32 v39, -v110, v32, v117
	v_fma_f32 v38, -v110, v32, v116
	v_fma_f32 v37, -v110, v32, v115
	v_fma_f32 v36, -v110, v32, v114
	v_fma_f32 v35, -v110, v32, v113
	v_fma_f32 v34, -v110, v32, v112
	v_fma_f32 v33, -v110, v32, v110
	v_fma_f32 v32, -v110, v32, v105
	s_waitcnt lgkmcnt(3)
	s_nop 0
	v_mfma_f32_32x32x16_bf16 v[32:47], v[136:139], v[48:51], v[32:47]
	s_nop 0
	s_waitcnt lgkmcnt(2)
	v_mfma_f32_32x32x16_bf16 v[32:47], v[140:143], v[52:55], v[32:47]
	s_nop 0
	s_waitcnt lgkmcnt(1)
	v_mfma_f32_32x32x16_bf16 v[32:47], v[144:147], v[56:59], v[32:47]
	s_nop 0
	s_waitcnt lgkmcnt(0)
	v_mfma_f32_32x32x16_bf16 v[32:47], v[148:151], v[60:63], v[32:47]
	s_cbranch_scc1 .LBB0_503
	s_cmp_eq_u32 s77, 0
	s_cselect_b64 s[96:97], -1, 0

; #define LAS __attribute__((address_space(3)))
; #define MFMA32(a, b, c) __builtin_amdgcn_mfma_f32_32x32x16_bf16((a), (b), (c), 0, 0, 0)
; template <int MODE> ...
;     ...
;         const float fb = slope * (float)(rr + 128 - 32 * kt);
;         f32x16 s;
; #pragma unroll
;         for (int i = 0; i < 16; ++i) s[i] = slope * (float)((i & 3) + 8 * (i >> 2)) - fb;
; #pragma unroll
;         for (int ks = 0; ks < 4; ++ks) s = MFMA32(*(const LAS bf16x8*)(kl + r * VROW + 32 * ks + 16 * h), qf[ks], s);
.LBB0_621:
	ds_read_b128 v[140:143], v131 offset:4608
	ds_read_b128 v[144:147], v131 offset:4640
	ds_read_b128 v[148:151], v131 offset:4672
	ds_read_b128 v[152:155], v131 offset:4704
	v_cvt_f32_i32_e32 v32, v137
	s_cmp_gt_i32 s91, 3
	s_mov_b64 s[2:3], -1
	v_fma_f32 v47, -v96, v32, v125
	v_fma_f32 v46, -v96, v32, v124
	v_fma_f32 v45, -v96, v32, v123
	v_fma_f32 v44, -v96, v32, v122
	v_fma_f32 v43, -v96, v32, v121
	v_fma_f32 v42, -v96, v32, v120
	v_fma_f32 v41, -v96, v32, v117
	v_fma_f32 v40, -v96, v32, v116
	v_fma_f32 v39, -v96, v32, v115
	v_fma_f32 v38, -v96, v32, v114
	v_fma_f32 v37, -v96, v32, v111
	v_fma_f32 v36, -v96, v32, v110
	v_fma_f32 v35, -v96, v32, v109
	v_fma_f32 v34, -v96, v32, v108
	v_fma_f32 v33, -v96, v32, v96
	v_fma_f32 v32, -v96, v32, v136
	s_waitcnt lgkmcnt(3)
	s_nop 0
	v_mfma_f32_32x32x16_bf16 v[32:47], v[140:143], v[48:51], v[32:47]
	s_nop 0
	s_waitcnt lgkmcnt(2)
	v_mfma_f32_32x32x16_bf16 v[32:47], v[144:147], v[52:55], v[32:47]
	s_nop 0
	s_waitcnt lgkmcnt(1)
	v_mfma_f32_32x32x16_bf16 v[32:47], v[148:151], v[56:59], v[32:47]
	s_nop 0
	s_waitcnt lgkmcnt(0)
	v_mfma_f32_32x32x16_bf16 v[32:47], v[152:155], v[60:63], v[32:47]
	s_cbranch_scc1 .LBB0_623
	s_cmp_eq_u32 s91, 0
	s_cselect_b64 s[2:3], -1, 0
